# K-loop: second B half-tile of K-tile t+2 staged one load segment later (6+2 LDS-DMA pieces become 4+4), SP2 wait vmcnt(6)
# baseline (speedup 1.0000x reference)
.LBB0_333:
	s_add_i32 s51, s50, 2
	s_add_u32 s52, s42, 0x80
	s_addc_u32 s53, s43, 0
	s_add_i32 s54, 0, 0x10000
	s_cmp_eq_u32 s87, s50
	s_cselect_b32 s79, s1, s53
	s_cselect_b32 s78, s0, s52
	v_add_u32_e32 v144, s54, v147
	s_cselect_b32 s53, s75, s49
	s_cselect_b32 s52, s74, s48
	s_add_i32 s50, 0, 0x14000
	s_waitcnt lgkmcnt(0)
	ds_read_b128 v[140:143], v144
	ds_read_b128 v[162:165], v144 offset:1024
	ds_read_b128 v[166:169], v144 offset:2048
	ds_read_b128 v[170:173], v144 offset:3072
	v_add_u32_e32 v144, s50, v147
	ds_read_b128 v[174:177], v144
	ds_read_b128 v[178:181], v144 offset:1024
	ds_read_b128 v[182:185], v144 offset:2048
	ds_read_b128 v[186:189], v144 offset:3072
	v_lshl_add_u64 v[144:145], s[42:43], 0, v[136:137]
	s_add_i32 m0, s9, 0xc000
	ds_read_b128 v[190:193], v149
	ds_read_b128 v[194:197], v149 offset:1024
	ds_read_b128 v[198:201], v149 offset:2048
	ds_read_b128 v[202:205], v149 offset:3072
	ds_read_b128 v[206:209], v149 offset:4096
	ds_read_b128 v[210:213], v149 offset:5120
	ds_read_b128 v[214:217], v149 offset:6144
	ds_read_b128 v[218:221], v149 offset:7168
	global_load_lds_dwordx4 v[144:145], off
	v_lshl_add_u64 v[144:145], s[42:43], 0, v[138:139]
	s_add_i32 m0, s9, 0xe000
	s_nop 0
	global_load_lds_dwordx4 v[144:145], off
	s_waitcnt vmcnt(8)
	s_waitcnt lgkmcnt(0)
	s_barrier
	s_setprio 1
	s_waitcnt lgkmcnt(0)
	v_mfma_f32_16x16x32_bf16 v[126:129], v[140:143], v[190:193], v[126:129]
	v_mfma_f32_16x16x32_bf16 v[122:125], v[166:169], v[190:193], v[122:125]
	v_mfma_f32_16x16x32_bf16 v[110:113], v[140:143], v[198:201], v[110:113]
	v_mfma_f32_16x16x32_bf16 v[106:109], v[166:169], v[198:201], v[106:109]
	v_mfma_f32_16x16x32_bf16 v[92:95], v[140:143], v[206:209], v[92:95]
	v_mfma_f32_16x16x32_bf16 v[88:91], v[166:169], v[206:209], v[88:91]
	v_mfma_f32_16x16x32_bf16 v[76:79], v[140:143], v[214:217], v[76:79]
	v_mfma_f32_16x16x32_bf16 v[72:75], v[166:169], v[214:217], v[72:75]
	v_mfma_f32_16x16x32_bf16 v[126:129], v[162:165], v[194:197], v[126:129]
	v_mfma_f32_16x16x32_bf16 v[122:125], v[170:173], v[194:197], v[122:125]
	v_mfma_f32_16x16x32_bf16 v[110:113], v[162:165], v[202:205], v[110:113]
	v_mfma_f32_16x16x32_bf16 v[106:109], v[170:173], v[202:205], v[106:109]
	v_mfma_f32_16x16x32_bf16 v[92:95], v[162:165], v[210:213], v[92:95]
	v_mfma_f32_16x16x32_bf16 v[88:91], v[170:173], v[210:213], v[88:91]
	v_mfma_f32_16x16x32_bf16 v[76:79], v[162:165], v[218:221], v[76:79]
	v_mfma_f32_16x16x32_bf16 v[72:75], v[170:173], v[218:221], v[72:75]
	s_setprio 0
	s_setprio 1
	v_mfma_f32_16x16x32_bf16 v[118:121], v[174:177], v[190:193], v[118:121]
	v_mfma_f32_16x16x32_bf16 v[114:117], v[182:185], v[190:193], v[114:117]
	v_mfma_f32_16x16x32_bf16 v[102:105], v[174:177], v[198:201], v[102:105]
	v_mfma_f32_16x16x32_bf16 v[98:101], v[182:185], v[198:201], v[98:101]
	v_mfma_f32_16x16x32_bf16 v[84:87], v[174:177], v[206:209], v[84:87]
	v_mfma_f32_16x16x32_bf16 v[80:83], v[182:185], v[206:209], v[80:83]
	v_mfma_f32_16x16x32_bf16 v[68:71], v[174:177], v[214:217], v[68:71]
	v_mfma_f32_16x16x32_bf16 v[64:67], v[182:185], v[214:217], v[64:67]
	v_mfma_f32_16x16x32_bf16 v[118:121], v[178:181], v[194:197], v[118:121]
	v_mfma_f32_16x16x32_bf16 v[114:117], v[186:189], v[194:197], v[114:117]
	v_mfma_f32_16x16x32_bf16 v[102:105], v[178:181], v[202:205], v[102:105]
	v_mfma_f32_16x16x32_bf16 v[98:101], v[186:189], v[202:205], v[98:101]
	v_mfma_f32_16x16x32_bf16 v[84:87], v[178:181], v[210:213], v[84:87]
	v_mfma_f32_16x16x32_bf16 v[80:83], v[186:189], v[210:213], v[80:83]
	v_mfma_f32_16x16x32_bf16 v[68:71], v[178:181], v[218:221], v[68:71]
	v_mfma_f32_16x16x32_bf16 v[64:67], v[186:189], v[218:221], v[64:67]
	s_setprio 0
	s_barrier
	s_add_i32 s54, s54, s8
	v_lshl_add_u64 v[144:145], s[52:53], 0, v[96:97]
	s_mov_b32 m0, s54
	ds_read_b128 v[190:193], v149 offset:16384
	ds_read_b128 v[194:197], v149 offset:17408
	ds_read_b128 v[198:201], v149 offset:18432
	ds_read_b128 v[202:205], v149 offset:19456
	ds_read_b128 v[206:209], v149 offset:20480
	ds_read_b128 v[210:213], v149 offset:21504
	ds_read_b128 v[214:217], v149 offset:22528
	ds_read_b128 v[218:221], v149 offset:23552
	global_load_lds_dwordx4 v[144:145], off
	s_add_i32 m0, s54, 0x2000
	v_lshl_add_u64 v[150:151], s[52:53], 0, v[134:135]
	s_add_u32 s52, s52, s34
	s_addc_u32 s53, s53, s35
	s_add_i32 s50, s50, s8
	global_load_lds_dwordx4 v[150:151], off
	v_lshl_add_u64 v[222:223], s[52:53], 0, v[96:97]
	v_lshl_add_u64 v[224:225], s[52:53], 0, v[134:135]
	v_lshl_add_u64 v[226:227], s[78:79], 0, v[130:131]
	s_mov_b32 m0, s9
	v_lshl_add_u64 v[228:229], s[78:79], 0, v[132:133]
	global_load_lds_dwordx4 v[226:227], off
	s_mov_b32 m0, s98
	s_nop 0
	global_load_lds_dwordx4 v[228:229], off
	s_waitcnt vmcnt(6)
	s_waitcnt lgkmcnt(0)
	s_barrier
	s_setprio 1
	s_waitcnt lgkmcnt(0)
	v_mfma_f32_16x16x32_bf16 v[60:63], v[140:143], v[190:193], v[60:63]
	v_mfma_f32_16x16x32_bf16 v[56:59], v[166:169], v[190:193], v[56:59]
	v_mfma_f32_16x16x32_bf16 v[44:47], v[140:143], v[198:201], v[44:47]
	v_mfma_f32_16x16x32_bf16 v[40:43], v[166:169], v[198:201], v[40:43]
	v_mfma_f32_16x16x32_bf16 v[28:31], v[140:143], v[206:209], v[28:31]
	v_mfma_f32_16x16x32_bf16 v[24:27], v[166:169], v[206:209], v[24:27]
	v_mfma_f32_16x16x32_bf16 v[12:15], v[140:143], v[214:217], v[12:15]
	v_mfma_f32_16x16x32_bf16 v[8:11], v[166:169], v[214:217], v[8:11]
	v_mfma_f32_16x16x32_bf16 v[60:63], v[162:165], v[194:197], v[60:63]
	v_mfma_f32_16x16x32_bf16 v[56:59], v[170:173], v[194:197], v[56:59]
	v_mfma_f32_16x16x32_bf16 v[44:47], v[162:165], v[202:205], v[44:47]
	v_mfma_f32_16x16x32_bf16 v[40:43], v[170:173], v[202:205], v[40:43]
	v_mfma_f32_16x16x32_bf16 v[28:31], v[162:165], v[210:213], v[28:31]
	v_mfma_f32_16x16x32_bf16 v[24:27], v[170:173], v[210:213], v[24:27]
	v_mfma_f32_16x16x32_bf16 v[12:15], v[162:165], v[218:221], v[12:15]
	v_mfma_f32_16x16x32_bf16 v[8:11], v[170:173], v[218:221], v[8:11]
	s_setprio 0
	s_setprio 1
	v_mfma_f32_16x16x32_bf16 v[52:55], v[174:177], v[190:193], v[52:55]
	v_mfma_f32_16x16x32_bf16 v[48:51], v[182:185], v[190:193], v[48:51]
	v_mfma_f32_16x16x32_bf16 v[36:39], v[174:177], v[198:201], v[36:39]
	v_mfma_f32_16x16x32_bf16 v[32:35], v[182:185], v[198:201], v[32:35]
	v_mfma_f32_16x16x32_bf16 v[20:23], v[174:177], v[206:209], v[20:23]
	v_mfma_f32_16x16x32_bf16 v[16:19], v[182:185], v[206:209], v[16:19]
	v_mfma_f32_16x16x32_bf16 v[4:7], v[174:177], v[214:217], v[4:7]
	v_mfma_f32_16x16x32_bf16 v[0:3], v[182:185], v[214:217], v[0:3]
	v_mfma_f32_16x16x32_bf16 v[52:55], v[178:181], v[194:197], v[52:55]
	v_mfma_f32_16x16x32_bf16 v[48:51], v[186:189], v[194:197], v[48:51]
	v_mfma_f32_16x16x32_bf16 v[36:39], v[178:181], v[202:205], v[36:39]
	v_mfma_f32_16x16x32_bf16 v[32:35], v[186:189], v[202:205], v[32:35]
	v_mfma_f32_16x16x32_bf16 v[20:23], v[178:181], v[210:213], v[20:23]
	v_mfma_f32_16x16x32_bf16 v[16:19], v[186:189], v[210:213], v[16:19]
	v_mfma_f32_16x16x32_bf16 v[4:7], v[178:181], v[218:221], v[4:7]
	v_mfma_f32_16x16x32_bf16 v[0:3], v[186:189], v[218:221], v[0:3]
	s_setprio 0
	s_barrier
	s_add_i32 s50, 0, 0x18000
	v_add_u32_e32 v161, s50, v147
	s_add_i32 s54, 0, 0x1c000
	ds_read_b128 v[140:143], v161
	ds_read_b128 v[162:165], v161 offset:1024
	ds_read_b128 v[166:169], v161 offset:2048
	ds_read_b128 v[170:173], v161 offset:3072
	v_add_u32_e32 v161, s54, v147
	ds_read_b128 v[174:177], v161
	ds_read_b128 v[178:181], v161 offset:1024
	ds_read_b128 v[182:185], v161 offset:2048
	ds_read_b128 v[186:189], v161 offset:3072
	s_add_u32 s52, s78, s34
	s_addc_u32 s53, s79, s35
	s_mov_b32 m0, s99
	v_lshl_add_u64 v[230:231], s[52:53], 0, v[130:131]
	ds_read_b128 v[190:193], v149 offset:32768
	ds_read_b128 v[194:197], v149 offset:33792
	ds_read_b128 v[198:201], v149 offset:34816
	ds_read_b128 v[202:205], v149 offset:35840
	ds_read_b128 v[206:209], v149 offset:36864
	ds_read_b128 v[210:213], v149 offset:37888
	ds_read_b128 v[214:217], v149 offset:38912
	ds_read_b128 v[218:221], v149 offset:39936
	s_add_i32 m0, s8, 0x14000
	s_nop 0
	global_load_lds_dwordx4 v[222:223], off
	s_add_i32 m0, m0, 0x2000
	s_nop 0
	global_load_lds_dwordx4 v[224:225], off
	s_mov_b32 m0, s99
	s_nop 0
	global_load_lds_dwordx4 v[230:231], off
	v_lshl_add_u64 v[230:231], s[52:53], 0, v[132:133]
	s_mov_b32 m0, s76
	s_nop 0
	global_load_lds_dwordx4 v[230:231], off
	s_waitcnt vmcnt(8)
	s_waitcnt lgkmcnt(0)
	s_barrier
	s_setprio 1
	s_waitcnt lgkmcnt(0)
	v_mfma_f32_16x16x32_bf16 v[126:129], v[140:143], v[190:193], v[126:129]
	v_mfma_f32_16x16x32_bf16 v[122:125], v[166:169], v[190:193], v[122:125]
	v_mfma_f32_16x16x32_bf16 v[110:113], v[140:143], v[198:201], v[110:113]
	v_mfma_f32_16x16x32_bf16 v[106:109], v[166:169], v[198:201], v[106:109]
	v_mfma_f32_16x16x32_bf16 v[92:95], v[140:143], v[206:209], v[92:95]
	v_mfma_f32_16x16x32_bf16 v[88:91], v[166:169], v[206:209], v[88:91]
	v_mfma_f32_16x16x32_bf16 v[76:79], v[140:143], v[214:217], v[76:79]
	v_mfma_f32_16x16x32_bf16 v[72:75], v[166:169], v[214:217], v[72:75]
	v_mfma_f32_16x16x32_bf16 v[126:129], v[162:165], v[194:197], v[126:129]
	v_mfma_f32_16x16x32_bf16 v[122:125], v[170:173], v[194:197], v[122:125]
	v_mfma_f32_16x16x32_bf16 v[110:113], v[162:165], v[202:205], v[110:113]
	v_mfma_f32_16x16x32_bf16 v[106:109], v[170:173], v[202:205], v[106:109]
	v_mfma_f32_16x16x32_bf16 v[92:95], v[162:165], v[210:213], v[92:95]
	v_mfma_f32_16x16x32_bf16 v[88:91], v[170:173], v[210:213], v[88:91]
	v_mfma_f32_16x16x32_bf16 v[76:79], v[162:165], v[218:221], v[76:79]
	v_mfma_f32_16x16x32_bf16 v[72:75], v[170:173], v[218:221], v[72:75]
	s_setprio 0
	s_setprio 1
	v_mfma_f32_16x16x32_bf16 v[118:121], v[174:177], v[190:193], v[118:121]
	v_mfma_f32_16x16x32_bf16 v[114:117], v[182:185], v[190:193], v[114:117]
	v_mfma_f32_16x16x32_bf16 v[102:105], v[174:177], v[198:201], v[102:105]
	v_mfma_f32_16x16x32_bf16 v[98:101], v[182:185], v[198:201], v[98:101]
	v_mfma_f32_16x16x32_bf16 v[84:87], v[174:177], v[206:209], v[84:87]
	v_mfma_f32_16x16x32_bf16 v[80:83], v[182:185], v[206:209], v[80:83]
	v_mfma_f32_16x16x32_bf16 v[68:71], v[174:177], v[214:217], v[68:71]
	v_mfma_f32_16x16x32_bf16 v[64:67], v[182:185], v[214:217], v[64:67]
	v_mfma_f32_16x16x32_bf16 v[118:121], v[178:181], v[194:197], v[118:121]
	v_mfma_f32_16x16x32_bf16 v[114:117], v[186:189], v[194:197], v[114:117]
	v_mfma_f32_16x16x32_bf16 v[102:105], v[178:181], v[202:205], v[102:105]
	v_mfma_f32_16x16x32_bf16 v[98:101], v[186:189], v[202:205], v[98:101]
	v_mfma_f32_16x16x32_bf16 v[84:87], v[178:181], v[210:213], v[84:87]
	v_mfma_f32_16x16x32_bf16 v[80:83], v[186:189], v[210:213], v[80:83]
	v_mfma_f32_16x16x32_bf16 v[68:71], v[178:181], v[218:221], v[68:71]
	v_mfma_f32_16x16x32_bf16 v[64:67], v[186:189], v[218:221], v[64:67]
	s_setprio 0
	s_barrier
	s_add_i32 s50, s50, s8
	v_lshl_add_u64 v[144:145], v[144:145], 0, s[12:13]
	s_mov_b32 m0, s50
	ds_read_b128 v[190:193], v149 offset:49152
	ds_read_b128 v[194:197], v149 offset:50176
	ds_read_b128 v[198:201], v149 offset:51200
	ds_read_b128 v[202:205], v149 offset:52224
	ds_read_b128 v[206:209], v149 offset:53248
	ds_read_b128 v[210:213], v149 offset:54272
	ds_read_b128 v[214:217], v149 offset:55296
	ds_read_b128 v[218:221], v149 offset:56320
	global_load_lds_dwordx4 v[144:145], off
	v_lshl_add_u64 v[144:145], v[150:151], 0, s[12:13]
	s_add_i32 m0, s50, 0x2000
	s_add_i32 s50, s54, s8
	global_load_lds_dwordx4 v[144:145], off
	v_lshl_add_u64 v[144:145], v[222:223], 0, s[12:13]
	s_mov_b32 m0, s50
	s_nop 0
	global_load_lds_dwordx4 v[144:145], off
	v_lshl_add_u64 v[144:145], v[224:225], 0, s[12:13]
	s_add_i32 m0, s50, 0x2000
	s_nop 0
	global_load_lds_dwordx4 v[144:145], off
	v_lshl_add_u64 v[144:145], v[226:227], 0, s[12:13]
	s_mov_b32 m0, s77
	s_nop 0
	global_load_lds_dwordx4 v[144:145], off
	v_lshl_add_u64 v[144:145], v[228:229], 0, s[12:13]
	s_mov_b32 m0, s86
	s_nop 0
	global_load_lds_dwordx4 v[144:145], off
	s_waitcnt vmcnt(8)
	s_waitcnt lgkmcnt(0)
	s_barrier
	s_setprio 1
	s_waitcnt lgkmcnt(0)
	v_mfma_f32_16x16x32_bf16 v[60:63], v[140:143], v[190:193], v[60:63]
	v_mfma_f32_16x16x32_bf16 v[56:59], v[166:169], v[190:193], v[56:59]
	v_mfma_f32_16x16x32_bf16 v[44:47], v[140:143], v[198:201], v[44:47]
	v_mfma_f32_16x16x32_bf16 v[40:43], v[166:169], v[198:201], v[40:43]
	v_mfma_f32_16x16x32_bf16 v[28:31], v[140:143], v[206:209], v[28:31]
	v_mfma_f32_16x16x32_bf16 v[24:27], v[166:169], v[206:209], v[24:27]
	v_mfma_f32_16x16x32_bf16 v[12:15], v[140:143], v[214:217], v[12:15]
	v_mfma_f32_16x16x32_bf16 v[8:11], v[166:169], v[214:217], v[8:11]
	v_mfma_f32_16x16x32_bf16 v[60:63], v[162:165], v[194:197], v[60:63]
	v_mfma_f32_16x16x32_bf16 v[56:59], v[170:173], v[194:197], v[56:59]
	v_mfma_f32_16x16x32_bf16 v[44:47], v[162:165], v[202:205], v[44:47]
	v_mfma_f32_16x16x32_bf16 v[40:43], v[170:173], v[202:205], v[40:43]
	v_mfma_f32_16x16x32_bf16 v[28:31], v[162:165], v[210:213], v[28:31]
	v_mfma_f32_16x16x32_bf16 v[24:27], v[170:173], v[210:213], v[24:27]
	v_mfma_f32_16x16x32_bf16 v[12:15], v[162:165], v[218:221], v[12:15]
	v_mfma_f32_16x16x32_bf16 v[8:11], v[170:173], v[218:221], v[8:11]
	s_setprio 0
	s_setprio 1
	v_mfma_f32_16x16x32_bf16 v[52:55], v[174:177], v[190:193], v[52:55]
	v_mfma_f32_16x16x32_bf16 v[48:51], v[182:185], v[190:193], v[48:51]
	v_mfma_f32_16x16x32_bf16 v[36:39], v[174:177], v[198:201], v[36:39]
	v_mfma_f32_16x16x32_bf16 v[32:35], v[182:185], v[198:201], v[32:35]
	v_mfma_f32_16x16x32_bf16 v[20:23], v[174:177], v[206:209], v[20:23]
	v_mfma_f32_16x16x32_bf16 v[16:19], v[182:185], v[206:209], v[16:19]
	v_mfma_f32_16x16x32_bf16 v[4:7], v[174:177], v[214:217], v[4:7]
	v_mfma_f32_16x16x32_bf16 v[0:3], v[182:185], v[214:217], v[0:3]
	v_mfma_f32_16x16x32_bf16 v[52:55], v[178:181], v[194:197], v[52:55]
	v_mfma_f32_16x16x32_bf16 v[48:51], v[186:189], v[194:197], v[48:51]
	v_mfma_f32_16x16x32_bf16 v[36:39], v[178:181], v[202:205], v[36:39]
	v_mfma_f32_16x16x32_bf16 v[32:35], v[186:189], v[202:205], v[32:35]
	v_mfma_f32_16x16x32_bf16 v[20:23], v[178:181], v[210:213], v[20:23]
	v_mfma_f32_16x16x32_bf16 v[16:19], v[186:189], v[210:213], v[16:19]
	v_mfma_f32_16x16x32_bf16 v[4:7], v[178:181], v[218:221], v[4:7]
	v_mfma_f32_16x16x32_bf16 v[0:3], v[186:189], v[218:221], v[0:3]
	s_setprio 0
	s_barrier
	s_add_u32 s42, s42, 0x100
	s_addc_u32 s43, s43, 0
	s_add_u32 s48, s48, 0x100
	s_addc_u32 s49, s49, 0
	s_cmp_ge_u32 s51, s64
	s_mov_b32 s50, s51
	s_cbranch_scc0 .LBB0_333
